# EpiIn: two store-only drains removed; row-stat exchanges: redundant acquire fence after the counter poll removed (slot traffic is agent-scope sc1)
# speedup vs baseline: 1.0074x; 1.0053x over previous
.LBB0_262:
	s_waitcnt lgkmcnt(0)
.LBB0_263:
	s_waitcnt vmcnt(0) lgkmcnt(0)
	s_barrier
	v_lshl_add_u32 v232, v194, 2, 0
	s_and_saveexec_b64 s[40:41], s[8:9]
	s_cbranch_execz .LBB0_265
	s_ashr_i32 s5, s4, 31
	s_lshl_b64 s[42:43], s[4:5], 12
	s_add_u32 s42, s56, s42
	s_addc_u32 s43, s57, s43
	s_waitcnt lgkmcnt(0)
	v_lshl_add_u64 v[198:199], v[194:195], 4, s[42:43]
	global_load_dword v200, v[198:199], off sc1
	global_load_dword v234, v[198:199], off offset:4 sc1
	global_load_dword v201, v[198:199], off offset:8 sc1
	global_load_dword v235, v[198:199], off offset:12 sc1
	v_add_u32_e32 v177, 0x21100, v232
	s_waitcnt vmcnt(0)
	v_pk_add_f32 v[198:199], v[200:201], v[234:235]
	s_nop 0
	v_add_f32_e32 v176, v198, v199
	v_fmamk_f32 v176, v176, 0x3a800000, v229
	v_rsq_f32_e32 v176, v176
	ds_write_b32 v177, v176

.LBB0_297:
	s_waitcnt lgkmcnt(0)
.LBB0_298:
	s_waitcnt vmcnt(0) lgkmcnt(0)
	s_barrier
	s_and_saveexec_b64 s[36:37], s[8:9]
	s_cbranch_execz .LBB0_300
	s_ashr_i32 s5, s4, 31
	s_lshl_b64 s[4:5], s[4:5], 12
	s_add_u32 s4, s60, s4
	s_addc_u32 s5, s61, s5
	v_lshl_add_u64 v[0:1], v[194:195], 4, s[4:5]
	s_waitcnt lgkmcnt(0)
	global_load_dword v2, v[0:1], off sc1
	global_load_dword v4, v[0:1], off offset:4 sc1
	global_load_dword v3, v[0:1], off offset:8 sc1
	global_load_dword v5, v[0:1], off offset:12 sc1
	s_waitcnt vmcnt(0)
	v_pk_add_f32 v[0:1], v[2:3], v[4:5]
	s_nop 0
	v_add_f32_e32 v0, v0, v1
	v_fmamk_f32 v0, v0, 0x3a800000, v229
	v_rsq_f32_e32 v0, v0
	v_add_u32_e32 v1, 0x22500, v232
	ds_write_b32 v1, v0

.LBB0_509:
	s_and_saveexec_b64 s[12:13], s[4:5]
	s_cbranch_execz .LBB0_511
	v_mul_f32_e32 v236, v18, v13
	v_mul_f32_e32 v238, v18, v12
	v_mov_b32_e32 v18, v23
	v_mov_b32_e32 v212, v9
	v_mov_b32_e32 v213, v11
	v_mul_f32_e32 v234, v22, v12
	v_mul_f32_e32 v240, v22, v13
	v_pk_mul_f32 v[242:243], v[18:19], v[14:15]
	v_mov_b32_e32 v22, v19
	v_mov_b32_e32 v210, v8
	v_mov_b32_e32 v211, v10
	v_pk_mul_f32 v[214:215], v[16:17], v[212:213]
	v_mov_b32_e32 v235, v242
	v_mov_b32_e32 v237, v243
	v_pk_mul_f32 v[18:19], v[22:23], v[14:15]
	v_pk_mul_f32 v[16:17], v[16:17], v[210:211]
	v_pk_fma_f32 v[210:211], v[20:21], v[210:211], v[214:215] neg_lo:[0,0,1] neg_hi:[0,0,1]
	v_pk_add_f32 v[214:215], v[234:235], v[236:237] neg_lo:[0,1] neg_hi:[0,1]
	v_mov_b32_e32 v241, v19
	v_mov_b32_e32 v239, v18
	v_pk_fma_f32 v[16:17], v[20:21], v[212:213], v[16:17]
	v_pk_add_f32 v[18:19], v[240:241], v[238:239]
	v_mov_b32_e32 v20, v210
	v_mov_b32_e32 v21, v211
	v_mov_b32_e32 v22, v214
	v_mov_b32_e32 v23, v215

.LBB0_513:
	s_cmp_eq_u32 s0, 4
	s_cselect_b64 vcc, -1, 0
	v_cndmask_b32_e32 v176, 1.0, v229, vcc
	v_cndmask_b32_e64 v206, v176, v230, s[14:15]
	v_pk_mul_f32 v[208:209], v[206:207], v[24:25] op_sel_hi:[0,1]
	v_pk_mul_f32 v[30:31], v[206:207], v[30:31] op_sel_hi:[0,1]
	v_pk_mul_f32 v[24:25], v[206:207], v[28:29] op_sel_hi:[0,1]
	v_pk_mul_f32 v[16:17], v[206:207], v[16:17] op_sel_hi:[0,1]
	v_pk_mul_f32 v[26:27], v[206:207], v[26:27] op_sel_hi:[0,1]
	v_cvt_pk_bf16_f32 v24, v24, v25
	v_cvt_pk_bf16_f32 v25, v30, v31
	v_cvt_pk_bf16_f32 v30, v16, v17
	v_pk_mul_f32 v[16:17], v[206:207], v[22:23] op_sel_hi:[0,1]
	v_cvt_pk_bf16_f32 v29, v26, v27
	v_pk_mul_f32 v[18:19], v[206:207], v[18:19] op_sel_hi:[0,1]
	v_cvt_pk_bf16_f32 v27, v16, v17
	v_mov_b64_e32 v[16:17], s[22:23]
	v_ashrrev_i32_e32 v199, 31, v198
	v_ashrrev_i32_e32 v201, 31, v200
	v_cvt_pk_bf16_f32 v31, v18, v19
	v_pk_mul_f32 v[18:19], v[206:207], v[20:21] op_sel_hi:[0,1]
	v_mad_i64_i32 v[16:17], s[0:1], v231, s66, v[16:17]
	v_cvt_pk_bf16_f32 v28, v208, v209
	v_cvt_pk_bf16_f32 v26, v18, v19
	v_lshl_add_u64 v[18:19], v[198:199], 1, v[16:17]
	v_lshl_add_u64 v[16:17], v[200:201], 1, v[16:17]
	global_store_dwordx4 v[18:19], v[24:27], off
	global_store_dwordx4 v[16:17], v[28:31], off
	v_mov_b32_e32 v16, v0
	v_mov_b32_e32 v210, v1
	v_mov_b32_e32 v17, v2
	v_mov_b32_e32 v211, v3
	v_mov_b32_e32 v20, v4
	v_mov_b32_e32 v209, v5
	v_mov_b32_e32 v30, v14
	v_mov_b32_e32 v31, v15
	v_mov_b32_e32 v28, v12
	v_mov_b32_e32 v29, v13
	v_mov_b32_e32 v18, v0
	v_mov_b32_e32 v19, v3
	v_mov_b32_e32 v214, v1
	v_mov_b32_e32 v215, v2
	v_mov_b32_e32 v212, v11
	v_mov_b32_e32 v213, v10
	v_mov_b32_e32 v24, v8
	v_mov_b32_e32 v25, v9
	s_and_saveexec_b64 s[14:15], s[4:5]
	s_cbranch_execz .LBB0_515
	v_mov_b32_e32 v18, v0
	v_mov_b32_e32 v19, v3
	v_mov_b32_e32 v16, v129
	v_mov_b32_e32 v17, v131
	v_mov_b32_e32 v0, v1
	v_mov_b32_e32 v1, v2
	v_mov_b32_e32 v2, v128
	v_mov_b32_e32 v3, v130
	v_pk_mul_f32 v[20:21], v[16:17], v[18:19]
	s_nop 0
	v_pk_fma_f32 v[210:211], v[2:3], v[0:1], v[20:21]
	v_pk_fma_f32 v[214:215], v[2:3], v[0:1], v[20:21] neg_lo:[0,0,1] neg_hi:[0,0,1]
	v_pk_mul_f32 v[0:1], v[16:17], v[0:1]
	v_mov_b32_e32 v214, v210
	v_pk_fma_f32 v[16:17], v[2:3], v[18:19], v[0:1] neg_lo:[0,0,1] neg_hi:[0,0,1]
	v_pk_fma_f32 v[18:19], v[2:3], v[18:19], v[0:1]
	v_pk_mul_f32 v[0:1], v[120:121], v[4:5] op_sel:[1,1] op_sel_hi:[1,0]
	v_pk_mul_f32 v[2:3], v[116:117], v[8:9] op_sel:[1,1] op_sel_hi:[1,0]
	v_pk_fma_f32 v[20:21], v[120:121], v[4:5], v[0:1] op_sel_hi:[0,1,1] neg_lo:[0,0,1] neg_hi:[0,0,1]
	v_pk_fma_f32 v[208:209], v[120:121], v[4:5], v[0:1] op_sel_hi:[0,1,1]
	v_mov_b32_e32 v0, v123
	v_pk_mul_f32 v[0:1], v[0:1], v[6:7] op_sel:[0,1] op_sel_hi:[0,0]
	v_pk_fma_f32 v[22:23], v[122:123], v[6:7], v[0:1] op_sel_hi:[0,1,1] neg_lo:[0,0,1] neg_hi:[0,0,1]
	v_pk_fma_f32 v[0:1], v[122:123], v[6:7], v[0:1] op_sel_hi:[0,1,1]
	v_mov_b32_e32 v0, v119
	v_pk_fma_f32 v[234:235], v[116:117], v[8:9], v[2:3] op_sel_hi:[0,1,1]
	v_pk_fma_f32 v[24:25], v[116:117], v[8:9], v[2:3] op_sel_hi:[0,1,1] neg_lo:[0,0,1] neg_hi:[0,0,1]
	v_pk_mul_f32 v[2:3], v[0:1], v[10:11] op_sel_hi:[0,1]
	v_pk_fma_f32 v[212:213], v[118:119], v[10:11], v[2:3] op_sel:[0,1,0] op_sel_hi:[0,0,1]
	v_pk_fma_f32 v[236:237], v[118:119], v[10:11], v[2:3] op_sel:[0,1,0] op_sel_hi:[0,0,1] neg_lo:[0,0,1] neg_hi:[0,0,1]
	v_pk_mul_f32 v[2:3], v[112:113], v[12:13] op_sel:[1,1] op_sel_hi:[1,0]
	v_mov_b32_e32 v0, v115
	v_pk_fma_f32 v[238:239], v[112:113], v[12:13], v[2:3] op_sel_hi:[0,1,1]
	v_pk_fma_f32 v[28:29], v[112:113], v[12:13], v[2:3] op_sel_hi:[0,1,1] neg_lo:[0,0,1] neg_hi:[0,0,1]
	v_pk_mul_f32 v[2:3], v[0:1], v[14:15] op_sel:[0,1] op_sel_hi:[0,0]
	v_pk_fma_f32 v[30:31], v[114:115], v[14:15], v[2:3] op_sel_hi:[0,1,1] neg_lo:[0,0,1] neg_hi:[0,0,1]
	v_pk_fma_f32 v[240:241], v[114:115], v[14:15], v[2:3] op_sel_hi:[0,1,1]
	v_mov_b32_e32 v17, v210
	v_mov_b32_e32 v18, v215
	v_mov_b32_e32 v21, v209
	v_mov_b32_e32 v23, v1
	v_mov_b32_e32 v25, v235
	v_mov_b32_e32 v26, v237
	v_mov_b32_e32 v27, v212
	v_mov_b32_e32 v29, v239
	v_mov_b32_e32 v31, v241
	v_mov_b64_e32 v[0:1], v[16:17]
	v_mov_b64_e32 v[2:3], v[18:19]
	v_mov_b64_e32 v[4:5], v[20:21]
	v_mov_b64_e32 v[6:7], v[22:23]
	v_mov_b64_e32 v[8:9], v[24:25]
	v_mov_b64_e32 v[10:11], v[26:27]
	v_mov_b64_e32 v[12:13], v[28:29]
	v_mov_b64_e32 v[14:15], v[30:31]
	v_mov_b32_e32 v17, v215
	v_mov_b32_e32 v211, v19
	v_mov_b32_e32 v18, v16
	v_mov_b32_e32 v213, v237

.LBB0_928:
.LBB0_929:
	s_waitcnt vmcnt(0) lgkmcnt(0)
	s_barrier
	v_lshl_add_u32 v228, v194, 2, 0
	s_and_saveexec_b64 s[44:45], s[8:9]
	s_cbranch_execz .LBB0_931
	s_ashr_i32 s5, s4, 31
	s_lshl_b64 s[46:47], s[4:5], 12
	s_add_u32 s46, s56, s46
	s_addc_u32 s47, s57, s47
	v_lshl_add_u64 v[230:231], v[194:195], 4, s[46:47]
	global_load_dword v232, v[230:231], off sc1
	global_load_dword v234, v[230:231], off offset:4 sc1
	global_load_dword v233, v[230:231], off offset:8 sc1
	global_load_dword v235, v[230:231], off offset:12 sc1
	v_add_u32_e32 v177, 0x21100, v228
	s_waitcnt vmcnt(0)
	v_pk_add_f32 v[230:231], v[232:233], v[234:235]
	s_nop 0
	v_add_f32_e32 v176, v230, v231
	v_fmamk_f32 v176, v176, 0x3a800000, v225
	v_rsq_f32_e32 v176, v176
	ds_write_b32 v177, v176

.LBB0_963:
	s_waitcnt lgkmcnt(0)
.LBB0_964:
	s_waitcnt vmcnt(0) lgkmcnt(0)
	s_barrier
	s_and_saveexec_b64 s[40:41], s[8:9]
	s_cbranch_execz .LBB0_966
	s_ashr_i32 s5, s4, 31
	s_lshl_b64 s[4:5], s[4:5], 12
	s_add_u32 s4, s60, s4
	s_addc_u32 s5, s61, s5
	v_lshl_add_u64 v[0:1], v[194:195], 4, s[4:5]
	s_waitcnt lgkmcnt(0)
	global_load_dword v2, v[0:1], off sc1
	global_load_dword v4, v[0:1], off offset:4 sc1
	global_load_dword v3, v[0:1], off offset:8 sc1
	global_load_dword v5, v[0:1], off offset:12 sc1
	s_waitcnt vmcnt(0)
	v_pk_add_f32 v[0:1], v[2:3], v[4:5]
	s_nop 0
	v_add_f32_e32 v0, v0, v1
	v_fmamk_f32 v0, v0, 0x3a800000, v225
	v_rsq_f32_e32 v0, v0
	v_add_u32_e32 v1, 0x22500, v228
	ds_write_b32 v1, v0

.LBB0_1260:
.LBB0_1261:
	s_waitcnt vmcnt(0) lgkmcnt(0)
	s_barrier
	s_and_saveexec_b64 s[28:29], s[8:9]
	s_cbranch_execz .LBB0_1263
	s_ashr_i32 s91, s90, 31
	s_lshl_b64 s[8:9], s[90:91], 12
	s_add_u32 s8, s42, s8
	s_addc_u32 s9, s43, s9
	v_lshl_add_u64 v[210:211], v[198:199], 4, s[8:9]
	global_load_dword v212, v[210:211], off sc1
	global_load_dword v214, v[210:211], off offset:4 sc1
	global_load_dword v213, v[210:211], off offset:8 sc1
	global_load_dword v215, v[210:211], off offset:12 sc1
	v_lshl_add_u32 v177, v198, 2, 0
	v_add_u32_e32 v177, 0x21100, v177
	s_waitcnt vmcnt(0)
	v_pk_add_f32 v[210:211], v[212:213], v[214:215]
	s_nop 0
	v_add_f32_e32 v176, v210, v211
	v_fmamk_f32 v176, v176, 0x3a800000, v207
	v_rsq_f32_e32 v176, v176
	ds_write_b32 v177, v176
